# P7a stage 2 reads each operand fragment once (12 instead of 24 LDS reads); attention queue hands out long units first
# speedup vs baseline: 1.0458x; 1.0088x over previous
; #define LAS __attribute__((address_space(3)))
; __device__ __forceinline__ void st_bf4(LAS bf16_t* p, f32x4 v) { u32x2 w; w.x = pk2(v.x, v.y); w.y = pk2(v.z, v.w); *(LAS u32x2*)p = w; }
; __device__ __forceinline__ void mm64(const LAS bf16_t* Aop, const LAS bf16_t* Bop, f32x4 (&acc)[2], int wave, int fr, int fq) {
;     const int a0 = 16 * (wave >> 1);
; #pragma unroll
;     for (int ks = 0; ks < 2; ++ks) {
;         const bf16x8 bfr = *(const LAS bf16x8*)(Bop + (a0 + fr) * MS + ks * 32 + fq * 8);
; #pragma unroll
;         for (int nt = 0; nt < 2; ++nt) { const int b0 = 32 * (wave & 1) + 16 * nt;
;             const bf16x8 afr = *(const LAS bf16x8*)(Aop + (b0 + fr) * MS + ks * 32 + fq * 8);
;             acc[nt] = __builtin_amdgcn_mfma_f32_16x16x32_bf16(afr, bfr, acc[nt], 0, 0, 0); }
;     }
; }
; __device__ __forceinline__ void chunk_pre(const Params& p, LAS unsigned char* lds, int item, int next_item, int tid, int wave, int lane, h16 (&raw)[48]) {
;     ...
;         for (int which = 0; which < 4; ++which) {
;             acc[0] = (f32x4){0.f, 0.f, 0.f, 0.f}; acc[1] = acc[0];
;             mm64((which & 1) ? Kt : Bt, (which & 2) ? Rt : At, acc, wave, fr, fq);
; #pragma unroll
;             for (int nt = 0; nt < 2; ++nt) { const int s0 = 32 * (wave & 1) + 16 * nt + 4 * fq; f32x4 v = acc[nt];
; #pragma unroll
;                 for (int jj = 0; jj < 4; ++jj) { const bool keep = (which & 2) ? (s0 + jj <= ar) : (s0 + jj < ar); if (!keep) v[jj] = 0.f; }
;                 if (which == 0) *(LAS f32x4*)(Mab + ar * 64 + s0) = v;
;                 else st_bf4(((which == 1) ? Mak : (which == 2) ? Mrb : Mrk) + ar * MS + s0, v); }
;         }
;     }
.LBB0_925:
	s_waitcnt lgkmcnt(0)
	s_barrier
	ds_read_b128 v[220:223], v91
	ds_read_b128 v[236:239], v161 offset:9216
	ds_read_b128 v[240:243], v161 offset:11520
	ds_read_b128 v[224:227], v91 offset:64
	ds_read_b128 v[184:187], v161 offset:9280
	ds_read_b128 v[188:191], v161 offset:11584
	ds_read_b128 v[192:195], v161 offset:18432
	ds_read_b128 v[196:199], v161 offset:20736
	ds_read_b128 v[200:203], v161 offset:18496
	ds_read_b128 v[206:209], v161 offset:20800
	ds_read_b128 v[228:231], v91 offset:27648
	ds_read_b128 v[232:235], v91 offset:27712
	s_or_b64 vcc, s[72:73], s[20:21]
	s_or_b64 s[80:81], s[76:77], s[24:25]
	s_waitcnt lgkmcnt(6)
	v_mfma_f32_16x16x32_bf16 v[8:11], v[236:239], v[220:223], 0
	v_mfma_f32_16x16x32_bf16 v[4:7], v[240:243], v[220:223], 0
	v_mfma_f32_16x16x32_bf16 v[8:11], v[184:187], v[224:227], v[8:11]
	v_mfma_f32_16x16x32_bf16 v[4:7], v[188:191], v[224:227], v[4:7]
	s_nop 7
	v_cndmask_b32_e64 v11, 0, v11, s[22:23]
	v_cndmask_b32_e64 v10, 0, v10, s[70:71]
	v_cndmask_b32_e64 v9, 0, v9, s[72:73]
	v_cndmask_b32_e32 v8, 0, v8, vcc
	v_cndmask_b32_e64 v7, 0, v7, s[26:27]
	v_cndmask_b32_e64 v6, 0, v6, s[74:75]
	v_cndmask_b32_e64 v5, 0, v5, s[76:77]
	v_cndmask_b32_e64 v4, 0, v4, s[80:81]
	ds_write_b128 v94, v[8:11]
	ds_write_b128 v94, v[4:7] offset:64
	s_waitcnt lgkmcnt(4)
	v_mfma_f32_16x16x32_bf16 v[8:11], v[192:195], v[220:223], 0
	v_mfma_f32_16x16x32_bf16 v[4:7], v[196:199], v[220:223], 0
	v_mfma_f32_16x16x32_bf16 v[8:11], v[200:203], v[224:227], v[8:11]
	v_mfma_f32_16x16x32_bf16 v[4:7], v[206:209], v[224:227], v[4:7]
	s_nop 7
	v_cndmask_b32_e64 v11, 0, v11, s[22:23]
	v_cndmask_b32_e64 v10, 0, v10, s[70:71]
	v_cndmask_b32_e64 v9, 0, v9, s[72:73]
	v_cndmask_b32_e32 v8, 0, v8, vcc
	v_cndmask_b32_e64 v7, 0, v7, s[26:27]
	v_cndmask_b32_e64 v6, 0, v6, s[74:75]
	v_cndmask_b32_e64 v5, 0, v5, s[76:77]
	v_cndmask_b32_e64 v4, 0, v4, s[80:81]
	v_cvt_pk_bf16_f32 v8, v8, v9
	v_cvt_pk_bf16_f32 v9, v10, v11
	v_cvt_pk_bf16_f32 v4, v4, v5
	v_cvt_pk_bf16_f32 v5, v6, v7
	v_add_u32_e32 v6, 0xf800, v95
	ds_write2_b64 v6, v[8:9], v[4:5] offset0:128 offset1:132
	s_waitcnt lgkmcnt(3)
	v_mfma_f32_16x16x32_bf16 v[8:11], v[236:239], v[228:231], 0
	v_mfma_f32_16x16x32_bf16 v[4:7], v[240:243], v[228:231], 0
	v_mfma_f32_16x16x32_bf16 v[8:11], v[184:187], v[232:235], v[8:11]
	v_mfma_f32_16x16x32_bf16 v[4:7], v[188:191], v[232:235], v[4:7]
	s_nop 7
	v_mov_b32_e32 v12, s9
	s_nop 3
	v_cndmask_b32_e64 v12, v8, v12, s[28:29]
	v_cndmask_b32_e64 v8, v12, v8, s[20:21]
	v_cndmask_b32_e64 v9, 0, v9, s[20:21]
	v_cndmask_b32_e64 v12, v10, 0, s[30:31]
	v_cvt_pk_bf16_f32 v10, v8, v9
	v_mov_b32_e32 v8, s9
	v_cndmask_b32_e64 v8, v4, v8, s[36:37]
	v_cndmask_b32_e64 v11, v11, 0, s[34:35]
	v_cndmask_b32_e64 v4, v8, v4, s[24:25]
	v_cndmask_b32_e64 v5, 0, v5, s[24:25]
	v_cndmask_b32_e64 v6, v6, 0, s[38:39]
	v_cndmask_b32_e64 v7, v7, 0, s[40:41]
	v_cvt_pk_bf16_f32 v11, v12, v11
	v_cvt_pk_bf16_f32 v4, v4, v5
	v_cvt_pk_bf16_f32 v5, v6, v7
	ds_write2_b64 v96, v[10:11], v[4:5] offset1:4
	s_waitcnt lgkmcnt(4)
	v_mfma_f32_16x16x32_bf16 v[8:11], v[192:195], v[228:231], 0
	v_mfma_f32_16x16x32_bf16 v[4:7], v[196:199], v[228:231], 0
	v_mfma_f32_16x16x32_bf16 v[8:11], v[200:203], v[232:235], v[8:11]
	v_mfma_f32_16x16x32_bf16 v[4:7], v[206:209], v[232:235], v[4:7]
	s_nop 7
	v_mov_b32_e32 v12, s9
	s_nop 3
	v_cndmask_b32_e64 v12, v8, v12, s[28:29]
	v_cndmask_b32_e64 v8, v12, v8, s[20:21]
	v_cndmask_b32_e64 v9, 0, v9, s[20:21]
	v_cndmask_b32_e64 v12, v10, 0, s[30:31]
	v_cvt_pk_bf16_f32 v10, v8, v9
	v_mov_b32_e32 v8, s9
	v_cndmask_b32_e64 v8, v4, v8, s[36:37]
	v_cndmask_b32_e64 v11, v11, 0, s[34:35]
	v_cndmask_b32_e64 v4, v8, v4, s[24:25]
	v_cndmask_b32_e64 v5, 0, v5, s[24:25]
	v_cndmask_b32_e64 v6, v6, 0, s[38:39]
	v_cndmask_b32_e64 v7, v7, 0, s[40:41]
	v_cvt_pk_bf16_f32 v11, v12, v11
	v_cvt_pk_bf16_f32 v4, v4, v5
	v_cvt_pk_bf16_f32 v5, v6, v7
	ds_write2_b64 v97, v[10:11], v[4:5] offset1:4
	s_waitcnt lgkmcnt(0)
	s_barrier
	ds_read_b128 v[4:7], v91 offset:55296
	ds_read_b128 v[8:11], v161 offset:64512
	ds_read_b128 v[12:15], v139 offset:64512
	s_waitcnt lgkmcnt(1)
	v_mfma_f32_16x16x32_bf16 v[8:11], v[8:11], v[4:7], 0
	s_waitcnt lgkmcnt(0)
	v_mfma_f32_16x16x32_bf16 v[4:7], v[12:15], v[4:7], 0
	ds_read_b128 v[12:15], v91 offset:55360
	ds_read_b128 v[16:19], v161 offset:64576
	s_waitcnt lgkmcnt(0)
	v_mfma_f32_16x16x32_bf16 v[8:11], v[16:19], v[12:15], v[8:11]
	ds_read_b128 v[16:19], v139 offset:64576
	s_waitcnt lgkmcnt(0)
	v_mfma_f32_16x16x32_bf16 v[4:7], v[16:19], v[12:15], v[4:7]
	s_nop 4
	v_cvt_pk_bf16_f32 v8, v8, v9
	v_cvt_pk_bf16_f32 v9, v10, v11
	s_nop 0
	v_cvt_pk_bf16_f32 v4, v4, v5
	v_cvt_pk_bf16_f32 v5, v6, v7
	ds_write2_b64 v140, v[8:9], v[4:5] offset1:4
	s_and_saveexec_b64 s[100:101], s[98:99]
	ds_write2_b64 v212, v[214:215], v[214:215] offset1:1
	s_mov_b64 exec, s[100:101]
	s_mov_b64 s[12:13], exec
	v_readlane_b32 s14, v244, 49
	v_readlane_b32 s15, v244, 50
	s_and_b64 s[14:15], s[12:13], s[14:15]
	s_mov_b64 exec, s[14:15]
	s_cbranch_execz .LBB0_935
; #define LAS __attribute__((address_space(3)))
; __device__ __forceinline__ unsigned pk2(float lo, float hi) { const f32x2c v = {lo, hi}; const bf16x2c b = __builtin_convertvector(v, bf16x2c); return __builtin_bit_cast(unsigned, b); }
; __device__ __forceinline__ void chunk_pre(const Params& p, LAS unsigned char* lds, int item, int next_item, int tid, int wave, int lane, h16 (&raw)[48]) {
;     ...
;     if (tid < 64) {
;         const int r = tid >> 4, j = tid & 15; float x[16];
; #pragma unroll
;         for (int i = 0; i < 16; ++i) x[i] = 0.f;
; #pragma unroll
;         for (int i = 0; i < 16; ++i) {
;             const LAS float* mrow = Mab + (16 * r + i) * 64 + 16 * r;
;             float v = (i == j) ? 1.f : 0.f;
; #pragma unroll
;             for (int q = 0; q < (i + 3) / 4; ++q) { const f32x4 m4 = *(const LAS f32x4*)(mrow + 4 * q);
;                 v += (m4.x * x[4 * q] + m4.y * x[4 * q + 1]) + (m4.z * x[4 * q + 2] + m4.w * x[4 * q + 3]); }
;             x[i] = v; TD[r * 256 + i * 16 + j] = v; Tb[(16 * r + i) * MS + 16 * r + j] = (bf16_t)(pk2(v, 0.f) & 0xffffu);
;         }
;     }
	v_mbcnt_lo_u32_b32 v203, -1, 0
	v_mbcnt_hi_u32_b32 v203, -1, v203
	v_lshrrev_b32_e32 v20, 4, v203
	v_and_b32_e32 v202, 15, v203
	v_lshlrev_b32_e32 v200, 8, v203
	v_lshl_add_u32 v200, v20, 6, v200
	v_add_u32_e32 v200, 0x16800, v200
	ds_read_b128 v[184:187], v200 offset:0
	ds_read_b128 v[188:191], v200 offset:16
	ds_read_b128 v[192:195], v200 offset:32
	ds_read_b128 v[196:199], v200 offset:48
	v_lshlrev_b32_e32 v201, 2, v202
	v_lshl_add_u32 v201, v20, 10, v201
	v_add_u32_e32 v201, 0x1f000, v201
	v_lshlrev_b32_e32 v202, 1, v202
	v_mov_b32_e32 v203, 0x920
	v_mad_u32_u24 v202, v20, v203, v202
	v_mov_b32_e32 v4, v101
	v_mov_b32_e32 v5, v103
	v_mov_b32_e32 v6, v104
	v_mov_b32_e32 v7, v105
	v_mov_b32_e32 v8, v106
	v_mov_b32_e32 v9, v107
	v_mov_b32_e32 v10, v108
	v_mov_b32_e32 v11, v109
	v_mov_b32_e32 v12, v110
	v_mov_b32_e32 v13, v111
	v_mov_b32_e32 v14, v112
	v_mov_b32_e32 v15, v113
	v_mov_b32_e32 v16, v114
	v_mov_b32_e32 v17, v115
	v_mov_b32_e32 v18, v116
	v_mov_b32_e32 v19, v117
	s_waitcnt lgkmcnt(0)
	v_fmac_f32_dpp v5, v184, v4 row_newbcast:1 row_mask:0xf bank_mask:0xf
	v_fmac_f32_dpp v6, v184, v4 row_newbcast:2 row_mask:0xf bank_mask:0xf
	v_fmac_f32_dpp v6, v185, v5 row_newbcast:2 row_mask:0xf bank_mask:0xf
	v_fmac_f32_dpp v7, v184, v4 row_newbcast:3 row_mask:0xf bank_mask:0xf
	v_fmac_f32_dpp v7, v185, v5 row_newbcast:3 row_mask:0xf bank_mask:0xf
	v_fmac_f32_dpp v7, v186, v6 row_newbcast:3 row_mask:0xf bank_mask:0xf
	v_fmac_f32_dpp v8, v184, v4 row_newbcast:4 row_mask:0xf bank_mask:0xf
	v_fmac_f32_dpp v8, v185, v5 row_newbcast:4 row_mask:0xf bank_mask:0xf
	v_fmac_f32_dpp v8, v186, v6 row_newbcast:4 row_mask:0xf bank_mask:0xf
	v_fmac_f32_dpp v8, v187, v7 row_newbcast:4 row_mask:0xf bank_mask:0xf
	v_fmac_f32_dpp v9, v184, v4 row_newbcast:5 row_mask:0xf bank_mask:0xf
	v_fmac_f32_dpp v9, v185, v5 row_newbcast:5 row_mask:0xf bank_mask:0xf
	v_fmac_f32_dpp v9, v186, v6 row_newbcast:5 row_mask:0xf bank_mask:0xf
	v_fmac_f32_dpp v9, v187, v7 row_newbcast:5 row_mask:0xf bank_mask:0xf
	v_fmac_f32_dpp v9, v188, v8 row_newbcast:5 row_mask:0xf bank_mask:0xf
	v_fmac_f32_dpp v10, v184, v4 row_newbcast:6 row_mask:0xf bank_mask:0xf
	v_fmac_f32_dpp v10, v185, v5 row_newbcast:6 row_mask:0xf bank_mask:0xf
	v_fmac_f32_dpp v10, v186, v6 row_newbcast:6 row_mask:0xf bank_mask:0xf
	v_fmac_f32_dpp v10, v187, v7 row_newbcast:6 row_mask:0xf bank_mask:0xf
	v_fmac_f32_dpp v10, v188, v8 row_newbcast:6 row_mask:0xf bank_mask:0xf
	v_fmac_f32_dpp v10, v189, v9 row_newbcast:6 row_mask:0xf bank_mask:0xf
	v_fmac_f32_dpp v11, v184, v4 row_newbcast:7 row_mask:0xf bank_mask:0xf
	v_fmac_f32_dpp v11, v185, v5 row_newbcast:7 row_mask:0xf bank_mask:0xf
	v_fmac_f32_dpp v11, v186, v6 row_newbcast:7 row_mask:0xf bank_mask:0xf
	v_fmac_f32_dpp v11, v187, v7 row_newbcast:7 row_mask:0xf bank_mask:0xf
	v_fmac_f32_dpp v11, v188, v8 row_newbcast:7 row_mask:0xf bank_mask:0xf
	v_fmac_f32_dpp v11, v189, v9 row_newbcast:7 row_mask:0xf bank_mask:0xf
	v_fmac_f32_dpp v11, v190, v10 row_newbcast:7 row_mask:0xf bank_mask:0xf
	v_fmac_f32_dpp v12, v184, v4 row_newbcast:8 row_mask:0xf bank_mask:0xf
	v_fmac_f32_dpp v12, v185, v5 row_newbcast:8 row_mask:0xf bank_mask:0xf
	v_fmac_f32_dpp v12, v186, v6 row_newbcast:8 row_mask:0xf bank_mask:0xf
	v_fmac_f32_dpp v12, v187, v7 row_newbcast:8 row_mask:0xf bank_mask:0xf
	v_fmac_f32_dpp v12, v188, v8 row_newbcast:8 row_mask:0xf bank_mask:0xf
	v_fmac_f32_dpp v12, v189, v9 row_newbcast:8 row_mask:0xf bank_mask:0xf
	v_fmac_f32_dpp v12, v190, v10 row_newbcast:8 row_mask:0xf bank_mask:0xf
	v_fmac_f32_dpp v12, v191, v11 row_newbcast:8 row_mask:0xf bank_mask:0xf
	v_fmac_f32_dpp v13, v184, v4 row_newbcast:9 row_mask:0xf bank_mask:0xf
	v_fmac_f32_dpp v13, v185, v5 row_newbcast:9 row_mask:0xf bank_mask:0xf
	v_fmac_f32_dpp v13, v186, v6 row_newbcast:9 row_mask:0xf bank_mask:0xf
	v_fmac_f32_dpp v13, v187, v7 row_newbcast:9 row_mask:0xf bank_mask:0xf
	v_fmac_f32_dpp v13, v188, v8 row_newbcast:9 row_mask:0xf bank_mask:0xf
	v_fmac_f32_dpp v13, v189, v9 row_newbcast:9 row_mask:0xf bank_mask:0xf
	v_fmac_f32_dpp v13, v190, v10 row_newbcast:9 row_mask:0xf bank_mask:0xf
	v_fmac_f32_dpp v13, v191, v11 row_newbcast:9 row_mask:0xf bank_mask:0xf
	v_fmac_f32_dpp v13, v192, v12 row_newbcast:9 row_mask:0xf bank_mask:0xf
	v_fmac_f32_dpp v14, v184, v4 row_newbcast:10 row_mask:0xf bank_mask:0xf
	v_fmac_f32_dpp v14, v185, v5 row_newbcast:10 row_mask:0xf bank_mask:0xf
	v_fmac_f32_dpp v14, v186, v6 row_newbcast:10 row_mask:0xf bank_mask:0xf
	v_fmac_f32_dpp v14, v187, v7 row_newbcast:10 row_mask:0xf bank_mask:0xf
	v_fmac_f32_dpp v14, v188, v8 row_newbcast:10 row_mask:0xf bank_mask:0xf
	v_fmac_f32_dpp v14, v189, v9 row_newbcast:10 row_mask:0xf bank_mask:0xf
	v_fmac_f32_dpp v14, v190, v10 row_newbcast:10 row_mask:0xf bank_mask:0xf
	v_fmac_f32_dpp v14, v191, v11 row_newbcast:10 row_mask:0xf bank_mask:0xf
	v_fmac_f32_dpp v14, v192, v12 row_newbcast:10 row_mask:0xf bank_mask:0xf
	v_fmac_f32_dpp v14, v193, v13 row_newbcast:10 row_mask:0xf bank_mask:0xf
	v_fmac_f32_dpp v15, v184, v4 row_newbcast:11 row_mask:0xf bank_mask:0xf
	v_fmac_f32_dpp v15, v185, v5 row_newbcast:11 row_mask:0xf bank_mask:0xf
	v_fmac_f32_dpp v15, v186, v6 row_newbcast:11 row_mask:0xf bank_mask:0xf
	v_fmac_f32_dpp v15, v187, v7 row_newbcast:11 row_mask:0xf bank_mask:0xf
	v_fmac_f32_dpp v15, v188, v8 row_newbcast:11 row_mask:0xf bank_mask:0xf
	v_fmac_f32_dpp v15, v189, v9 row_newbcast:11 row_mask:0xf bank_mask:0xf
	v_fmac_f32_dpp v15, v190, v10 row_newbcast:11 row_mask:0xf bank_mask:0xf
	v_fmac_f32_dpp v15, v191, v11 row_newbcast:11 row_mask:0xf bank_mask:0xf
	v_fmac_f32_dpp v15, v192, v12 row_newbcast:11 row_mask:0xf bank_mask:0xf
; #define LAS __attribute__((address_space(3)))
; __device__ __forceinline__ unsigned pk2(float lo, float hi) { const f32x2c v = {lo, hi}; const bf16x2c b = __builtin_convertvector(v, bf16x2c); return __builtin_bit_cast(unsigned, b); }
; __device__ __forceinline__ void chunk_pre(const Params& p, LAS unsigned char* lds, int item, int next_item, int tid, int wave, int lane, h16 (&raw)[48]) {
;     ...
;     if (tid < 64) {
;         const int r = tid >> 4, j = tid & 15; float x[16];
; #pragma unroll
;         for (int i = 0; i < 16; ++i) x[i] = 0.f;
; #pragma unroll
;         for (int i = 0; i < 16; ++i) {
;             const LAS float* mrow = Mab + (16 * r + i) * 64 + 16 * r;
;             float v = (i == j) ? 1.f : 0.f;
; #pragma unroll
;             for (int q = 0; q < (i + 3) / 4; ++q) { const f32x4 m4 = *(const LAS f32x4*)(mrow + 4 * q);
;                 v += (m4.x * x[4 * q] + m4.y * x[4 * q + 1]) + (m4.z * x[4 * q + 2] + m4.w * x[4 * q + 3]); }
;             x[i] = v; TD[r * 256 + i * 16 + j] = v; Tb[(16 * r + i) * MS + 16 * r + j] = (bf16_t)(pk2(v, 0.f) & 0xffffu);
;         }
;     }
	v_fmac_f32_dpp v15, v193, v13 row_newbcast:11 row_mask:0xf bank_mask:0xf
	v_fmac_f32_dpp v15, v194, v14 row_newbcast:11 row_mask:0xf bank_mask:0xf
	v_fmac_f32_dpp v16, v184, v4 row_newbcast:12 row_mask:0xf bank_mask:0xf
	v_fmac_f32_dpp v16, v185, v5 row_newbcast:12 row_mask:0xf bank_mask:0xf
	v_fmac_f32_dpp v16, v186, v6 row_newbcast:12 row_mask:0xf bank_mask:0xf
	v_fmac_f32_dpp v16, v187, v7 row_newbcast:12 row_mask:0xf bank_mask:0xf
	v_fmac_f32_dpp v16, v188, v8 row_newbcast:12 row_mask:0xf bank_mask:0xf
	v_fmac_f32_dpp v16, v189, v9 row_newbcast:12 row_mask:0xf bank_mask:0xf
	v_fmac_f32_dpp v16, v190, v10 row_newbcast:12 row_mask:0xf bank_mask:0xf
	v_fmac_f32_dpp v16, v191, v11 row_newbcast:12 row_mask:0xf bank_mask:0xf
	v_fmac_f32_dpp v16, v192, v12 row_newbcast:12 row_mask:0xf bank_mask:0xf
	v_fmac_f32_dpp v16, v193, v13 row_newbcast:12 row_mask:0xf bank_mask:0xf
	v_fmac_f32_dpp v16, v194, v14 row_newbcast:12 row_mask:0xf bank_mask:0xf
	v_fmac_f32_dpp v16, v195, v15 row_newbcast:12 row_mask:0xf bank_mask:0xf
	v_fmac_f32_dpp v17, v184, v4 row_newbcast:13 row_mask:0xf bank_mask:0xf
	v_fmac_f32_dpp v17, v185, v5 row_newbcast:13 row_mask:0xf bank_mask:0xf
	v_fmac_f32_dpp v17, v186, v6 row_newbcast:13 row_mask:0xf bank_mask:0xf
	v_fmac_f32_dpp v17, v187, v7 row_newbcast:13 row_mask:0xf bank_mask:0xf
	v_fmac_f32_dpp v17, v188, v8 row_newbcast:13 row_mask:0xf bank_mask:0xf
	v_fmac_f32_dpp v17, v189, v9 row_newbcast:13 row_mask:0xf bank_mask:0xf
	v_fmac_f32_dpp v17, v190, v10 row_newbcast:13 row_mask:0xf bank_mask:0xf
	v_fmac_f32_dpp v17, v191, v11 row_newbcast:13 row_mask:0xf bank_mask:0xf
	v_fmac_f32_dpp v17, v192, v12 row_newbcast:13 row_mask:0xf bank_mask:0xf
	v_fmac_f32_dpp v17, v193, v13 row_newbcast:13 row_mask:0xf bank_mask:0xf
	v_fmac_f32_dpp v17, v194, v14 row_newbcast:13 row_mask:0xf bank_mask:0xf
	v_fmac_f32_dpp v17, v195, v15 row_newbcast:13 row_mask:0xf bank_mask:0xf
	v_fmac_f32_dpp v17, v196, v16 row_newbcast:13 row_mask:0xf bank_mask:0xf
	v_fmac_f32_dpp v18, v184, v4 row_newbcast:14 row_mask:0xf bank_mask:0xf
	v_fmac_f32_dpp v18, v185, v5 row_newbcast:14 row_mask:0xf bank_mask:0xf
	v_fmac_f32_dpp v18, v186, v6 row_newbcast:14 row_mask:0xf bank_mask:0xf
	v_fmac_f32_dpp v18, v187, v7 row_newbcast:14 row_mask:0xf bank_mask:0xf
	v_fmac_f32_dpp v18, v188, v8 row_newbcast:14 row_mask:0xf bank_mask:0xf
	v_fmac_f32_dpp v18, v189, v9 row_newbcast:14 row_mask:0xf bank_mask:0xf
	v_fmac_f32_dpp v18, v190, v10 row_newbcast:14 row_mask:0xf bank_mask:0xf
	v_fmac_f32_dpp v18, v191, v11 row_newbcast:14 row_mask:0xf bank_mask:0xf
	v_fmac_f32_dpp v18, v192, v12 row_newbcast:14 row_mask:0xf bank_mask:0xf
	v_fmac_f32_dpp v18, v193, v13 row_newbcast:14 row_mask:0xf bank_mask:0xf
	v_fmac_f32_dpp v18, v194, v14 row_newbcast:14 row_mask:0xf bank_mask:0xf
	v_fmac_f32_dpp v18, v195, v15 row_newbcast:14 row_mask:0xf bank_mask:0xf
	v_fmac_f32_dpp v18, v196, v16 row_newbcast:14 row_mask:0xf bank_mask:0xf
	v_fmac_f32_dpp v18, v197, v17 row_newbcast:14 row_mask:0xf bank_mask:0xf
	v_fmac_f32_dpp v19, v184, v4 row_newbcast:15 row_mask:0xf bank_mask:0xf
	v_fmac_f32_dpp v19, v185, v5 row_newbcast:15 row_mask:0xf bank_mask:0xf
	v_fmac_f32_dpp v19, v186, v6 row_newbcast:15 row_mask:0xf bank_mask:0xf
	v_fmac_f32_dpp v19, v187, v7 row_newbcast:15 row_mask:0xf bank_mask:0xf
	v_fmac_f32_dpp v19, v188, v8 row_newbcast:15 row_mask:0xf bank_mask:0xf
	v_fmac_f32_dpp v19, v189, v9 row_newbcast:15 row_mask:0xf bank_mask:0xf
	v_fmac_f32_dpp v19, v190, v10 row_newbcast:15 row_mask:0xf bank_mask:0xf
	v_fmac_f32_dpp v19, v191, v11 row_newbcast:15 row_mask:0xf bank_mask:0xf
	v_fmac_f32_dpp v19, v192, v12 row_newbcast:15 row_mask:0xf bank_mask:0xf
	v_fmac_f32_dpp v19, v193, v13 row_newbcast:15 row_mask:0xf bank_mask:0xf
	v_fmac_f32_dpp v19, v194, v14 row_newbcast:15 row_mask:0xf bank_mask:0xf
	v_fmac_f32_dpp v19, v195, v15 row_newbcast:15 row_mask:0xf bank_mask:0xf
	v_fmac_f32_dpp v19, v196, v16 row_newbcast:15 row_mask:0xf bank_mask:0xf
	v_fmac_f32_dpp v19, v197, v17 row_newbcast:15 row_mask:0xf bank_mask:0xf
	v_fmac_f32_dpp v19, v198, v18 row_newbcast:15 row_mask:0xf bank_mask:0xf
	ds_write_b32 v201, v4 offset:0
	v_cvt_pk_bf16_f32 v20, v4, v4
	ds_write_b16 v202, v20 offset:0
	ds_write_b32 v201, v5 offset:64
	v_cvt_pk_bf16_f32 v20, v5, v5
	ds_write_b16 v202, v20 offset:144
	ds_write_b32 v201, v6 offset:128
	v_cvt_pk_bf16_f32 v20, v6, v6
	ds_write_b16 v202, v20 offset:288
	ds_write_b32 v201, v7 offset:192
	v_cvt_pk_bf16_f32 v20, v7, v7
	ds_write_b16 v202, v20 offset:432
	ds_write_b32 v201, v8 offset:256
	v_cvt_pk_bf16_f32 v20, v8, v8
	ds_write_b16 v202, v20 offset:576
	ds_write_b32 v201, v9 offset:320
	v_cvt_pk_bf16_f32 v20, v9, v9
	ds_write_b16 v202, v20 offset:720
	ds_write_b32 v201, v10 offset:384
	v_cvt_pk_bf16_f32 v20, v10, v10
	ds_write_b16 v202, v20 offset:864
	ds_write_b32 v201, v11 offset:448
	v_cvt_pk_bf16_f32 v20, v11, v11
	ds_write_b16 v202, v20 offset:1008
	ds_write_b32 v201, v12 offset:512
	v_cvt_pk_bf16_f32 v20, v12, v12
	ds_write_b16 v202, v20 offset:1152
	ds_write_b32 v201, v13 offset:576
	v_cvt_pk_bf16_f32 v20, v13, v13
	ds_write_b16 v202, v20 offset:1296
	ds_write_b32 v201, v14 offset:640
	v_cvt_pk_bf16_f32 v20, v14, v14
	ds_write_b16 v202, v20 offset:1440
	ds_write_b32 v201, v15 offset:704
	v_cvt_pk_bf16_f32 v20, v15, v15
	ds_write_b16 v202, v20 offset:1584
	ds_write_b32 v201, v16 offset:768
	v_cvt_pk_bf16_f32 v20, v16, v16
	ds_write_b16 v202, v20 offset:1728
	ds_write_b32 v201, v17 offset:832
	v_cvt_pk_bf16_f32 v20, v17, v17
	ds_write_b16 v202, v20 offset:1872
	ds_write_b32 v201, v18 offset:896
	v_cvt_pk_bf16_f32 v20, v18, v18
	ds_write_b16 v202, v20 offset:2016
	ds_write_b32 v201, v19 offset:960
	v_cvt_pk_bf16_f32 v20, v19, v19
	ds_write_b16 v202, v20 offset:2160

; #define LAS __attribute__((address_space(3)))
; #define lane (lane_now())
; __device__ __forceinline__ void attn_unit(const Params& p, const LAS float* bl, LAS bf16_t* stg, int unit, int lane) {
;     const bf16_t* PB = (const bf16_t*)(p.ws + WS_PB); bf16_t* MIX = (bf16_t*)(p.ws + WS_MIX);
;     const int half = unit & 1, cq = (unit >> 1) & 127, bh = unit >> 8, b = bh >> 3, h = bh & 7;
;     const int r32 = lane & 31, hi = lane >> 5;
;     const unsigned loff = (unsigned)(((lane >> 3) * NPB + (lane & 7) * 8) * 2);
;     ...
;     const size_t tok0 = (size_t)b * SEQ;
;     const bf16_t* qblk = PB + (tok0 + cq * 64) * NPB + h * 64;
;     bf16x8 qf[4];
; #pragma unroll
;     for (int d0 = 0; d0 < 4; ++d0) qf[d0] = __builtin_bit_cast(bf16x8, *FRAGP(qblk, half * 4 + d0));
;     f32x16 o0 = {}, o1 = {}; float lsum = 0.f;
;     const LAS float* blh = bl + h * 513;
;     const int qi = half * 32 + r32;
;     u32x4 kc[8], vc[8];
;     const int dl0 = (cq < 8 ? cq : 8);
;     { const bf16_t* kblk = PB + (tok0 + (size_t)(cq - dl0) * 64) * NPB + 512 + h * 64;
; #pragma unroll
;       for (int f = 0; f < 8; ++f) kc[f] = *FRAGP(kblk, f); }
;     ...
;         const size_t krow0 = tok0 + (size_t)(cq - dlt) * 64;
;         { const bf16_t* vblk = PB + krow0 * NPB + 1024 + h * 64;
; #pragma unroll
;           for (int f = 0; f < 8; ++f) vc[f] = *FRAGP(vblk, f); }
;         __builtin_amdgcn_sched_barrier(0);
;         f32x16 s0, s1;
;         if (dlt >= 5) {
;             const float bc = blh[512];
; #pragma unroll
;             for (int r = 0; r < 16; ++r) { s0[r] = bc; s1[r] = bc; }
;         } else if (dlt == 4) {
;             const int base = dlt * 64 + qi + 256;
; #pragma unroll
; __global__ void __launch_bounds__(512, 2) mega_fwd(Params p) {
;     ...
;         for (unsigned qi = 0; qi < 8u; ++qi) {
;             const unsigned qx = (myx + qi) & 7u; unsigned* qctr = qbase + 64 * qx;
;             for (;;) {
;                 unsigned u = 0u;
;                 if (lane8a == 0) u = __hip_atomic_fetch_add(qctr, 1u, __ATOMIC_RELAXED, __HIP_MEMORY_SCOPE_AGENT);
;                 u = (unsigned)__builtin_amdgcn_readfirstlane((int)u);
;                 if (u >= 4u * 256u) break;
;                 attn_unit(p, bl, (LAS bf16_t*)(lds + 73728 + wave * (32 * MS * 2)), (int)(((qx + 8u * (u >> 8)) << 8) | (u & 255u)), lane8a);
.LBB0_1029:
	s_or_b64 exec, exec, s[12:13]
	v_readfirstlane_b32 s0, v0
	s_cmpk_gt_u32 s0, 0x3ff
	s_mov_b64 s[12:13], -1
	s_cbranch_scc1 .LBB0_1024
	s_and_b32 s12, s0, 1
	s_bfe_u32 s14, s0, 0x70001
	s_sub_u32 s14, 0x7f, s14
	s_lshl_b32 s0, s0, 5
	s_and_b32 s13, s0, 0x6000
	s_lshl_b32 s0, s14, 6
	s_or_b32 s11, s0, s13
	s_mul_i32 s0, s11, 0xc00
	v_lshl_add_u64 v[0:1], v[158:159], 0, s[0:1]
	s_mul_i32 s0, s12, 0x18000
	v_lshl_add_u64 v[0:1], v[0:1], 0, s[0:1]
	v_add_co_u32_e32 v2, vcc, 0x6000, v0
	s_min_u32 s16, s14, 8
	s_nop 0
	v_addc_co_u32_e32 v3, vcc, 0, v1, vcc
	global_load_dwordx4 v[64:67], v[0:1], off
	global_load_dwordx4 v[68:71], v[2:3], off
	v_add_co_u32_e32 v2, vcc, 0xc000, v0
	s_lshl_b32 s0, s12, 5
	s_nop 0
	v_addc_co_u32_e32 v3, vcc, 0, v1, vcc
	s_sub_i32 s12, s14, s16
	v_add_co_u32_e32 v0, vcc, s20, v0
	s_lshl_b32 s12, s12, 6
	s_nop 0
	v_addc_co_u32_e32 v1, vcc, 0, v1, vcc
	s_add_i32 s12, s12, s13
	global_load_dwordx4 v[72:75], v[2:3], off
	global_load_dwordx4 v[76:79], v[0:1], off
	v_mad_i64_i32 v[0:1], s[12:13], s12, v175, v[158:159]
	v_add_co_u32_e32 v2, vcc, s21, v0
	s_lshl_b32 s12, s16, 8
	s_nop 0
	v_addc_co_u32_e32 v3, vcc, 0, v1, vcc
	global_load_dwordx4 v[80:83], v[0:1], off offset:1024
	global_load_dwordx4 v[84:87], v[2:3], off offset:1024
	v_add_co_u32_e32 v2, vcc, s23, v0
	s_add_i32 s12, s38, s12
	s_nop 0
	v_addc_co_u32_e32 v3, vcc, 0, v1, vcc
	v_add_co_u32_e32 v4, vcc, s20, v0
	s_cmp_lt_u32 s14, 8
	s_nop 0
	v_addc_co_u32_e32 v5, vcc, 0, v1, vcc
	global_load_dwordx4 v[88:91], v[2:3], off offset:1024
	global_load_dwordx4 v[92:95], v[4:5], off offset:1024
	v_add_co_u32_e32 v2, vcc, s22, v0
	v_mov_b32_e32 v209, 0
	s_nop 0
	v_addc_co_u32_e32 v3, vcc, 0, v1, vcc
	v_add_co_u32_e32 v4, vcc, s24, v0
	v_mov_b32_e32 v6, v209
	s_nop 0
	v_addc_co_u32_e32 v5, vcc, 0, v1, vcc
	global_load_dwordx4 v[96:99], v[2:3], off offset:1024
	global_load_dwordx4 v[100:103], v[4:5], off offset:1024
	v_add_co_u32_e32 v2, vcc, s25, v0
	v_mov_b32_e32 v4, v209
	s_nop 0
	v_addc_co_u32_e32 v3, vcc, 0, v1, vcc
	v_add_co_u32_e32 v0, vcc, s26, v0
	v_mov_b32_e32 v5, v209
	s_nop 0
	v_addc_co_u32_e32 v1, vcc, 0, v1, vcc
	global_load_dwordx4 v[104:107], v[2:3], off offset:1024
	global_load_dwordx4 v[108:111], v[0:1], off offset:1024
	v_or_b32_e32 v0, s0, v167
	v_or_b32_e32 v0, 0x200, v0
	v_sub_u32_e32 v1, v0, v168
	v_min_i32_e32 v2, 0x200, v1
	v_min_i32_e32 v3, 0x220, v1
	v_lshl_add_u32 v176, v2, 2, s37
	v_lshl_add_u32 v2, v3, 2, s37
	v_add_u32_e32 v177, 0xffffff80, v2
	v_add_u32_e32 v2, v0, v169
	v_min_i32_e32 v3, 0x200, v2
	v_min_i32_e32 v2, 0x220, v2
	v_lshl_add_u32 v2, v2, 2, s37
	v_add_u32_e32 v179, 0xffffff80, v2
	v_sub_u32_e32 v2, v0, v170
	v_lshl_add_u32 v178, v3, 2, s37
	v_min_i32_e32 v3, 0x200, v2
	v_min_i32_e32 v2, 0x220, v2
	v_lshl_add_u32 v2, v2, 2, s37
	v_sub_u32_e32 v0, v0, v171
	v_lshl_add_u32 v180, v3, 2, s37
	v_add_u32_e32 v181, 0xffffff80, v2
	v_min_i32_e32 v2, 0x200, v0
	v_min_i32_e32 v3, 0x220, v0
	v_lshl_add_u32 v182, v2, 2, s37
	v_lshl_add_u32 v2, v3, 2, s37
	v_add_u32_e32 v183, 0xffffff80, v2
	v_add_u32_e32 v2, -8, v1
	v_min_i32_e32 v3, 0x200, v2
	v_min_i32_e32 v2, 0x220, v2
	v_lshl_add_u32 v2, v2, 2, s37
	v_add_u32_e32 v185, 0xffffff80, v2
	v_add_u32_e32 v2, -9, v1
	v_lshl_add_u32 v184, v3, 2, s37
	v_min_i32_e32 v3, 0x200, v2
	v_min_i32_e32 v2, 0x220, v2
	v_lshl_add_u32 v2, v2, 2, s37
	v_add_u32_e32 v187, 0xffffff80, v2
	v_add_u32_e32 v2, -10, v1
	v_lshl_add_u32 v186, v3, 2, s37
	v_min_i32_e32 v3, 0x200, v2
	v_min_i32_e32 v2, 0x220, v2
	v_lshl_add_u32 v2, v2, 2, s37
	v_add_u32_e32 v189, 0xffffff80, v2
	v_add_u32_e32 v2, -8, v0
	v_lshl_add_u32 v188, v3, 2, s37
	v_min_i32_e32 v3, 0x200, v2
	v_min_i32_e32 v2, 0x220, v2
	v_lshl_add_u32 v2, v2, 2, s37
	v_add_u32_e32 v191, 0xffffff80, v2
	v_add_u32_e32 v2, -16, v1
	v_lshl_add_u32 v190, v3, 2, s37
	v_min_i32_e32 v3, 0x200, v2
	v_min_i32_e32 v2, 0x220, v2
	v_lshl_add_u32 v2, v2, 2, s37
	v_add_u32_e32 v193, 0xffffff80, v2
	v_subrev_u32_e32 v2, 17, v1
	v_lshl_add_u32 v192, v3, 2, s37
	v_min_i32_e32 v3, 0x200, v2
	v_min_i32_e32 v2, 0x220, v2
	v_lshl_add_u32 v2, v2, 2, s37
	v_add_u32_e32 v195, 0xffffff80, v2
	v_subrev_u32_e32 v2, 18, v1
	v_lshl_add_u32 v194, v3, 2, s37
	v_min_i32_e32 v3, 0x200, v2
	v_min_i32_e32 v2, 0x220, v2
	v_lshl_add_u32 v2, v2, 2, s37
	v_add_u32_e32 v197, 0xffffff80, v2
	v_add_u32_e32 v2, -16, v0
	v_lshl_add_u32 v196, v3, 2, s37
	v_min_i32_e32 v3, 0x200, v2
	v_min_i32_e32 v2, 0x220, v2
	v_lshl_add_u32 v2, v2, 2, s37
	v_add_u32_e32 v199, 0xffffff80, v2
	v_subrev_u32_e32 v2, 24, v1
	v_lshl_add_u32 v198, v3, 2, s37
	v_min_i32_e32 v3, 0x200, v2
	v_min_i32_e32 v2, 0x220, v2
	v_lshl_add_u32 v2, v2, 2, s37
	v_add_u32_e32 v201, 0xffffff80, v2
	v_subrev_u32_e32 v2, 25, v1
	v_lshl_add_u32 v200, v3, 2, s37
	v_min_i32_e32 v3, 0x200, v2
	v_min_i32_e32 v2, 0x220, v2
	v_lshl_add_u32 v2, v2, 2, s37
	v_subrev_u32_e32 v1, 26, v1
	v_add_u32_e32 v203, 0xffffff80, v2
	v_min_i32_e32 v2, 0x200, v1
	v_min_i32_e32 v1, 0x220, v1
	v_lshl_add_u32 v1, v1, 2, s37
	v_subrev_u32_e32 v0, 24, v0
	v_add_u32_e32 v205, 0xffffff80, v1
	v_min_i32_e32 v1, 0x200, v0
	v_min_i32_e32 v0, 0x220, v0
	v_lshl_add_u32 v0, v0, 2, s37
	v_add_u32_e32 v207, 0xffffff80, v0
	v_add_u32_e32 v0, s0, v173
	v_lshl_add_u32 v208, v0, 2, s12
	s_cselect_b32 s12, s14, 8
	s_mul_i32 s17, s12, 0x30000
	s_lshl_b32 s12, s12, 6
	s_sub_i32 s12, s11, s12
	v_mad_i64_i32 v[162:163], s[12:13], s12, v175, v[160:161]
	v_lshl_add_u32 v202, v3, 2, s37
	v_lshl_add_u32 v204, v2, 2, s37
	v_lshl_add_u32 v206, v1, 2, s37
	v_readfirstlane_b32 s98, v162
	v_readfirstlane_b32 s99, v163
	s_nop 1
	v_subrev_u32_e32 v226, s98, v162
	v_add_u32_e32 v227, 0x6000, v226
	v_add_u32_e32 v228, 0xc000, v226
	v_add_u32_e32 v229, 0x12000, v226
	v_add_u32_e32 v230, 0x18000, v226
	v_add_u32_e32 v231, 0x1e000, v226
	v_add_u32_e32 v232, 0x24000, v226
	v_add_u32_e32 v233, 0x2a000, v226
	s_add_u32 s39, s17, 0xfff40000
	s_add_u32 s40, s17, 0x30000
	s_mov_b64 s[12:13], 0
	v_mov_b32_e32 v0, 0
	v_mov_b32_e32 v1, v209
	v_mov_b32_e32 v2, v209
	v_mov_b32_e32 v3, v209
	v_mov_b32_e32 v7, v209
	v_mov_b32_e32 v8, v209
	v_mov_b32_e32 v9, v209
	v_mov_b32_e32 v10, v209
	v_mov_b32_e32 v11, v209
	v_mov_b32_e32 v12, v209
	v_mov_b32_e32 v13, v209
	v_mov_b32_e32 v14, v209
	v_mov_b32_e32 v15, v209
	v_mov_b32_e32 v16, 0
	v_mov_b32_e32 v17, v209
	v_mov_b32_e32 v18, v209
	v_mov_b32_e32 v19, v209
	v_mov_b32_e32 v20, v209
	v_mov_b32_e32 v21, v209
	v_mov_b32_e32 v22, v209
	v_mov_b32_e32 v23, v209
	v_mov_b32_e32 v24, v209
	v_mov_b32_e32 v25, v209
	v_mov_b32_e32 v26, v209
	v_mov_b32_e32 v27, v209
	v_mov_b32_e32 v28, v209
	v_mov_b32_e32 v29, v209
	v_mov_b32_e32 v30, v209
	v_mov_b32_e32 v31, v209
	s_branch .LBB0_1032
